# seam 5: groups whose ACT rows lie beyond U (pm >= 24) only wait for 'every workgroup left P4'; others keep the 'all P5 K-loops done' wait; stagger s_sleep 10
# speedup vs baseline: 1.0238x; 1.0238x over previous
; __device__ __forceinline__ unsigned xb_ld(unsigned* p)              { return __hip_atomic_load(p, __ATOMIC_RELAXED, __HIP_MEMORY_SCOPE_AGENT); }
; __device__ __forceinline__ unsigned xb_add(unsigned* p, unsigned v) { return __hip_atomic_fetch_add(p, v, __ATOMIC_RELAXED, __HIP_MEMORY_SCOPE_AGENT); }
; #define XB_SPIN(cond, bar) do { unsigned _sp = 0; while (cond) { __builtin_amdgcn_s_sleep(1); \
;     if ((++_sp & 255u) == 0u) { if (xb_ld(&(bar)[XB_TMO])) break; if (_sp > XB_SPIN_CAP) { atomicAdd(&(bar)[XB_TMO], 1u); break; } } } } while (0)
; #define SEAM(k) do { if (IN(k) && IN((k) + 1)) GRID_SYNC(); } while (0)
; __device__ __forceinline__ void xcd_barrier(const XcdBarrier& b) {
;     asm volatile("s_waitcnt vmcnt(0)" ::: "memory");
;     __syncthreads();
;     if (threadIdx.x == 0) {
;         unsigned* bar = b.bar;
;         __builtin_amdgcn_s_waitcnt(0);
;         unsigned nloc = b.st[0], nx = b.st[1];
;         if (nloc == 0u) { xcd_barrier_complete(bar, b.x, nloc, nx); b.st[0] = nloc; b.st[1] = nx; }
;         const unsigned old = xb_add(&bar[XB_XSUB(b.x)], 1u);
;         const unsigned gen = old / nloc;
;         if (old + 1u == (gen + 1u) * nloc) {
;             __builtin_amdgcn_fence(__ATOMIC_RELEASE, "agent");
;             asm volatile("s_waitcnt vmcnt(0)" ::: "memory");
;             const unsigned og = xb_add(&bar[XB_TOP], 1u);
;             const unsigned tg = og / nx;
;             if (og + 1u == (tg + 1u) * nx) xb_add(&bar[XB_TOPGEN], 1u);
;             else XB_SPIN(xb_ld(&bar[XB_TOPGEN]) == tg, bar);
;             __builtin_amdgcn_fence(__ATOMIC_ACQUIRE, "agent");
;             xb_add(&bar[XB_XGEN(b.x)], 1u);
;             asm volatile("s_waitcnt vmcnt(0)" ::: "memory");
;         } else {
;             XB_SPIN(xb_ld(&bar[XB_XGEN(b.x)]) == gen, bar);
;             __builtin_amdgcn_fence(__ATOMIC_ACQUIRE, "agent");
;             asm volatile("s_waitcnt vmcnt(0)" ::: "memory");
;         }
;     }
;     __syncthreads();
; }
; __global__ void __launch_bounds__(NTHR, 2) mk_fwd(MkArgs a) {
;     ...
;     SEAM(4);
.Lgb4_poll:
	s_sleep 1
	global_load_dword v2, v0, s[90:91] sc1
	s_waitcnt vmcnt(0)
	v_cmp_gt_u32_e32 vcc, 4, v2
	s_cbranch_vccnz .Lgb4_poll
	v_mov_b32_e32 v0, 0x3c44
	v_mov_b32_e32 v1, 1
	global_atomic_add v0, v1, s[90:91]
	s_branch .LBB9_644

; __device__ __forceinline__ unsigned xb_ld(unsigned* p)              { return __hip_atomic_load(p, __ATOMIC_RELAXED, __HIP_MEMORY_SCOPE_AGENT); }
; __device__ __forceinline__ unsigned xb_add(unsigned* p, unsigned v) { return __hip_atomic_fetch_add(p, v, __ATOMIC_RELAXED, __HIP_MEMORY_SCOPE_AGENT); }
; #define XB_SPIN(cond, bar) do { unsigned _sp = 0; while (cond) { __builtin_amdgcn_s_sleep(1); \
;     if ((++_sp & 255u) == 0u) { if (xb_ld(&(bar)[XB_TMO])) break; if (_sp > XB_SPIN_CAP) { atomicAdd(&(bar)[XB_TMO], 1u); break; } } } } while (0)
; #define SEAM(k) do { if (IN(k) && IN((k) + 1)) GRID_SYNC(); } while (0)
; __device__ __forceinline__ void xcd_barrier(const XcdBarrier& b) {
;     asm volatile("s_waitcnt vmcnt(0)" ::: "memory");
;     __syncthreads();
;     if (threadIdx.x == 0) {
;         unsigned* bar = b.bar;
;         __builtin_amdgcn_s_waitcnt(0);
;         unsigned nloc = b.st[0], nx = b.st[1];
;         if (nloc == 0u) { xcd_barrier_complete(bar, b.x, nloc, nx); b.st[0] = nloc; b.st[1] = nx; }
;         const unsigned old = xb_add(&bar[XB_XSUB(b.x)], 1u);
;         const unsigned gen = old / nloc;
;         if (old + 1u == (gen + 1u) * nloc) {
;             __builtin_amdgcn_fence(__ATOMIC_RELEASE, "agent");
;             asm volatile("s_waitcnt vmcnt(0)" ::: "memory");
;             const unsigned og = xb_add(&bar[XB_TOP], 1u);
;             const unsigned tg = og / nx;
;             if (og + 1u == (tg + 1u) * nx) xb_add(&bar[XB_TOPGEN], 1u);
;             else XB_SPIN(xb_ld(&bar[XB_TOPGEN]) == tg, bar);
;             __builtin_amdgcn_fence(__ATOMIC_ACQUIRE, "agent");
;             xb_add(&bar[XB_XGEN(b.x)], 1u);
;             asm volatile("s_waitcnt vmcnt(0)" ::: "memory");
;         } else {
;             XB_SPIN(xb_ld(&bar[XB_XGEN(b.x)]) == gen, bar);
;             __builtin_amdgcn_fence(__ATOMIC_ACQUIRE, "agent");
;             asm volatile("s_waitcnt vmcnt(0)" ::: "memory");
;         }
;     }
;     __syncthreads();
; }
; __global__ void __launch_bounds__(NTHR, 2) mk_fwd(MkArgs a) {
;     ...
;     SEAM(5);
.LBB9_706:
	s_cmp_gt_i32 s93, 6
	s_cselect_b64 s[0:1], -1, 0
	s_and_b64 s[2:3], s[8:9], s[0:1]
	s_andn2_b64 vcc, exec, s[2:3]
	s_cbranch_vccnz .LBB9_760
	s_waitcnt vmcnt(0)
	s_waitcnt vmcnt(0) lgkmcnt(0)
	s_barrier
	s_and_saveexec_b64 s[4:5], s[80:81]
	s_cbranch_execz .LBB9_759
	v_mov_b32_e32 v0, 0x24008
	ds_read_b32 v0, v0
	s_waitcnt lgkmcnt(0)
	v_readfirstlane_b32 s98, v0
	s_nop 3
	s_cmp_eq_u32 s98, 1
	s_cbranch_scc0 .Lgb5_orig
	s_cmpk_lg_i32 s94, 0x100
	s_cbranch_scc1 .Lgb5_orig
	s_and_b32 s98, s97, 63
	s_lshl_b32 s98, s98, 2
	s_add_i32 s98, s98, 0x3d00
	v_mov_b32_e32 v0, s98
	v_mov_b32_e32 v1, 0x100
	global_atomic_add v0, v1, s[90:91]
	buffer_inv sc1
	s_and_b32 s98, s97, 7
	s_lshl_b32 s98, s98, 3
	s_bfe_u32 s99, s97, 0x30003
	s_or_b32 s98, s98, s99
	s_movk_i32 s99, 0x3c40
	s_cmp_ge_u32 s98, 24
	s_cselect_b32 s98, 0x3c44, s99
	v_mov_b32_e32 v1, s98
